# p3scanbal2: as p3scanbal, but the second state-scan trip goes to the LoRA blocks with the lightest epilogues (bid 192-255: sigmoid/identity groups) instead of the heaviest
# speedup vs baseline: 1.0057x; 1.0053x over previous
.LBB0_583:
	s_mov_b32 s98, s69
	s_mov_b32 s99, s96
	s_cmpk_lg_i32 s96, 0x100
	s_cbranch_scc1 .Lss_go
	s_cmp_lt_u32 s69, 64
	s_cbranch_scc1 .LBB0_589
	s_sub_i32 s100, s69, 192
	s_cmp_ge_u32 s69, 192
	s_cselect_b32 s69, s100, s69
	s_movk_i32 s96, 0xc0
